# NSA compressed pass 1: running row sum with packed sub/add and one select on m per tile instead of per-element compare/select
# speedup vs baseline: 1.0019x; 1.0019x over previous
; __device__ __forceinline__ float ex2(float x) { return __builtin_amdgcn_exp2f(x); }
; __device__ __forceinline__ void nsa_unit(const Params& p, LAS unsigned char* lds, int b, int hkv, int i, int tid, int lane, int wave) {
;     ...
;         mx = fmaxf(mx, __shfl_xor(mx, 32));
;         const float mn = fmaxf(m, mx);
;         float ps = 0.f;
; #pragma unroll
;         for (int r = 0; r < 16; ++r) { ps += (s0[r] > -1.0e29f ? ex2(s0[r] - mn) : 0.f) + (s1[r] > -1.0e29f ? ex2(s1[r] - mn) : 0.f); }
;         l = l * ex2(m - mn) + ps; m = mn;
.LBB0_473:
	s_waitcnt lgkmcnt(1)
	ds_bpermute_b32 v4, v201, v95
	s_addk_i32 s4, 0x4000
	s_addk_i32 s11, 0xfc00
	s_add_i32 s0, s0, 64
	s_waitcnt lgkmcnt(0)
	v_max3_f32 v178, v94, v95, v4
	s_add_i32 s5, s5, 1
	v_lshl_add_u64 v[88:89], v[88:89], 0, s[38:39]
	v_sub_f32_e32 v9, v94, v178
	v_cmp_lt_f32_e32 vcc, s95, v178
	v_pk_add_f32 v[34:35], v[34:35], v[178:179] op_sel_hi:[1,0] neg_lo:[0,1] neg_hi:[0,1]
	v_pk_add_f32 v[36:37], v[36:37], v[178:179] op_sel_hi:[1,0] neg_lo:[0,1] neg_hi:[0,1]
	v_pk_add_f32 v[38:39], v[38:39], v[178:179] op_sel_hi:[1,0] neg_lo:[0,1] neg_hi:[0,1]
	v_pk_add_f32 v[40:41], v[40:41], v[178:179] op_sel_hi:[1,0] neg_lo:[0,1] neg_hi:[0,1]
	v_pk_add_f32 v[42:43], v[42:43], v[178:179] op_sel_hi:[1,0] neg_lo:[0,1] neg_hi:[0,1]
	v_pk_add_f32 v[44:45], v[44:45], v[178:179] op_sel_hi:[1,0] neg_lo:[0,1] neg_hi:[0,1]
	v_pk_add_f32 v[46:47], v[46:47], v[178:179] op_sel_hi:[1,0] neg_lo:[0,1] neg_hi:[0,1]
	v_pk_add_f32 v[48:49], v[48:49], v[178:179] op_sel_hi:[1,0] neg_lo:[0,1] neg_hi:[0,1]
	v_pk_add_f32 v[50:51], v[50:51], v[178:179] op_sel_hi:[1,0] neg_lo:[0,1] neg_hi:[0,1]
	v_pk_add_f32 v[52:53], v[52:53], v[178:179] op_sel_hi:[1,0] neg_lo:[0,1] neg_hi:[0,1]
	v_pk_add_f32 v[54:55], v[54:55], v[178:179] op_sel_hi:[1,0] neg_lo:[0,1] neg_hi:[0,1]
	v_pk_add_f32 v[56:57], v[56:57], v[178:179] op_sel_hi:[1,0] neg_lo:[0,1] neg_hi:[0,1]
	v_pk_add_f32 v[58:59], v[58:59], v[178:179] op_sel_hi:[1,0] neg_lo:[0,1] neg_hi:[0,1]
	v_pk_add_f32 v[60:61], v[60:61], v[178:179] op_sel_hi:[1,0] neg_lo:[0,1] neg_hi:[0,1]
	v_pk_add_f32 v[62:63], v[62:63], v[178:179] op_sel_hi:[1,0] neg_lo:[0,1] neg_hi:[0,1]
	v_pk_add_f32 v[64:65], v[64:65], v[178:179] op_sel_hi:[1,0] neg_lo:[0,1] neg_hi:[0,1]
	v_exp_f32_e32 v9, v9
	v_exp_f32_e32 v34, v34
	v_exp_f32_e32 v35, v35
	v_exp_f32_e32 v36, v36
	v_exp_f32_e32 v37, v37
	v_exp_f32_e32 v38, v38
	v_exp_f32_e32 v39, v39
	v_exp_f32_e32 v40, v40
	v_exp_f32_e32 v41, v41
	v_exp_f32_e32 v42, v42
	v_exp_f32_e32 v43, v43
	v_exp_f32_e32 v44, v44
	v_exp_f32_e32 v45, v45
	v_exp_f32_e32 v46, v46
	v_exp_f32_e32 v47, v47
	v_exp_f32_e32 v48, v48
	v_exp_f32_e32 v49, v49
	v_exp_f32_e32 v50, v50
	v_exp_f32_e32 v51, v51
	v_exp_f32_e32 v52, v52
	v_exp_f32_e32 v53, v53
	v_exp_f32_e32 v54, v54
	v_exp_f32_e32 v55, v55
	v_exp_f32_e32 v56, v56
	v_exp_f32_e32 v57, v57
	v_exp_f32_e32 v58, v58
	v_exp_f32_e32 v59, v59
	v_exp_f32_e32 v60, v60
	v_exp_f32_e32 v61, v61
	v_exp_f32_e32 v62, v62
	v_exp_f32_e32 v63, v63
	v_exp_f32_e32 v64, v64
	v_exp_f32_e32 v65, v65
	v_pk_add_f32 v[34:35], v[34:35], v[36:37]
	v_pk_add_f32 v[38:39], v[38:39], v[40:41]
	v_pk_add_f32 v[42:43], v[42:43], v[44:45]
	v_pk_add_f32 v[46:47], v[46:47], v[48:49]
	v_pk_add_f32 v[50:51], v[50:51], v[52:53]
	v_pk_add_f32 v[54:55], v[54:55], v[56:57]
	v_pk_add_f32 v[58:59], v[58:59], v[60:61]
	v_pk_add_f32 v[62:63], v[62:63], v[64:65]
	v_pk_add_f32 v[34:35], v[34:35], v[38:39]
	v_pk_add_f32 v[42:43], v[42:43], v[46:47]
	v_pk_add_f32 v[50:51], v[50:51], v[54:55]
	v_pk_add_f32 v[58:59], v[58:59], v[62:63]
	v_pk_add_f32 v[34:35], v[34:35], v[42:43]
	v_pk_add_f32 v[50:51], v[50:51], v[58:59]
	v_pk_add_f32 v[34:35], v[34:35], v[50:51]
	v_add_f32_e32 v4, v34, v35
	v_cndmask_b32_e32 v4, 0, v4, vcc
	v_fmac_f32_e32 v4, v93, v9
	s_cmp_eq_u32 s12, 0
	s_cbranch_scc1 .LBB0_477
	s_mov_b32 s13, s12
	v_mov_b32_e32 v94, v178
	v_mov_b32_e32 v93, v4
	s_add_i32 s12, s13, -1
	s_cmp_lt_i32 s12, 2
	s_mov_b64 s[2:3], -1
	s_cbranch_scc1 .LBB0_462
